# group1: 8 of 15 grid barriers replaced by row-block-local 8-workgroup barriers (rows of row phases remapped so each chain stays inside its 8-WG group); remaining global barriers re-numbered
# speedup vs baseline: 1.0238x; 1.0238x over previous
.LBB0_111:
	s_or_b64 exec, exec, s[4:5]
	s_add_u32 s30, s56, 0x3400000
	s_addc_u32 s31, s57, 0
	s_and_b32 s98, s78, 31
	s_lshl_b32 s98, s98, 3
	s_lshr_b32 s99, s78, 5
	s_or_b32 s98, s98, s99
	v_lshl_add_u32 v145, s98, 3, v148
	s_movk_i32 s0, 0x800
	v_mbcnt_lo_u32_b32 v163, -1, 0
	v_lshlrev_b32_e32 v166, 2, v148
	s_waitcnt lgkmcnt(0)
	s_barrier
	v_cmp_gt_i32_e64 s[0:1], s0, v145
	s_mov_b64 s[4:5], exec
	s_nop 0
	v_writelane_b32 v219, s0, 31
	s_nop 1
	v_writelane_b32 v219, s1, 32
	s_and_b64 s[0:1], s[4:5], s[0:1]
	s_mov_b64 exec, s[0:1]
	s_cbranch_execz .LBB0_124
	v_mbcnt_hi_u32_b32 v1, -1, v163
	v_and_b32_e32 v2, 64, v1
	v_add_u32_e32 v2, 64, v2
	v_xor_b32_e32 v3, 32, v1
	v_cmp_lt_i32_e32 vcc, v3, v2
	v_and_b32_e32 v0, 0x1f8, v144
	v_mov_b32_e32 v33, 0
	v_cndmask_b32_e32 v3, v1, v3, vcc
	v_lshlrev_b32_e32 v62, 2, v3
	v_xor_b32_e32 v3, 16, v1
	v_cmp_lt_i32_e32 vcc, v3, v2
	v_lshlrev_b32_e32 v32, 1, v0
	v_readlane_b32 s8, v219, 9
	v_cndmask_b32_e32 v3, v1, v3, vcc
	v_lshlrev_b32_e32 v63, 2, v3
	v_xor_b32_e32 v3, 8, v1
	v_cmp_lt_i32_e32 vcc, v3, v2
	v_lshl_add_u64 v[34:35], s[30:31], 0, v[32:33]
	v_lshlrev_b32_e32 v32, 2, v0
	v_cndmask_b32_e32 v3, v1, v3, vcc
	v_lshlrev_b32_e32 v64, 2, v3
	v_xor_b32_e32 v3, 4, v1
	v_cmp_lt_i32_e32 vcc, v3, v2
	v_readlane_b32 s9, v219, 10
	v_readlane_b32 s10, v219, 11
	v_cndmask_b32_e32 v3, v1, v3, vcc
	v_lshlrev_b32_e32 v65, 2, v3
	v_xor_b32_e32 v3, 2, v1
	v_cmp_lt_i32_e32 vcc, v3, v2
	v_readlane_b32 s11, v219, 12
	v_readlane_b32 s12, v219, 13
	v_cndmask_b32_e32 v3, v1, v3, vcc
	v_lshlrev_b32_e32 v66, 2, v3
	v_xor_b32_e32 v3, 1, v1
	v_cmp_lt_i32_e32 vcc, v3, v2
	v_or_b32_e32 v2, 0x200, v0
	v_readlane_b32 s13, v219, 14
	v_cndmask_b32_e32 v1, v1, v3, vcc
	v_lshlrev_b32_e32 v67, 2, v1
	s_lshl_b32 s0, s58, 3
	v_lshl_add_u64 v[36:37], s[12:13], 0, v[32:33]
	s_and_b32 s98, s78, 31
	s_lshl_b32 s98, s98, 3
	s_lshr_b32 s99, s78, 5
	s_or_b32 s98, s98, s99
	v_lshl_add_u32 v68, s98, 5, v166
	s_lshl_b32 s1, s58, 5
	s_mov_b64 s[6:7], 0
	v_mov_b32_e32 v69, 0xfffff000
	s_movk_i32 s2, 0x3ff
	s_mov_b64 s[8:9], 0x1000
	v_lshlrev_b32_e32 v32, 2, v0
	v_lshlrev_b32_e32 v38, 2, v2
	v_mov_b32_e32 v39, v33
	s_movk_i32 s3, 0xfff
	v_mov_b32_e32 v70, 0x358637bd
	s_mov_b32 s10, 0x800000
	s_movk_i32 s11, 0x7ff
	v_mov_b32_e32 v71, v145
	v_readlane_b32 s14, v219, 15
	v_readlane_b32 s15, v219, 16
	v_readlane_b32 s16, v219, 17
	v_readlane_b32 s17, v219, 18
	v_readlane_b32 s18, v219, 19
	v_readlane_b32 s19, v219, 20
	v_readlane_b32 s20, v219, 21
	v_readlane_b32 s21, v219, 22
	v_readlane_b32 s22, v219, 23
	v_readlane_b32 s23, v219, 24
	s_branch .LBB0_114

.LBB0_124:
	s_or_b64 exec, exec, s[4:5]
	s_waitcnt vmcnt(0)
	s_barrier
	s_mov_b64 s[4:5], exec
	v_readlane_b32 s0, v219, 25
	v_readlane_b32 s1, v219, 26
	s_and_b64 s[0:1], s[4:5], s[0:1]
	s_mov_b64 exec, s[0:1]
	s_cbranch_execz .LBB0_176
	v_readlane_b32 s0, v219, 27
	v_readlane_b32 s1, v219, 28
	v_readlane_b32 s2, v219, 30
	s_waitcnt vmcnt(0) lgkmcnt(0)
	buffer_inv sc1
	s_and_b32 s2, s2, 31
	s_lshl_b32 s2, s2, 7
	s_add_i32 s2, s2, 64
	v_mov_b32_e32 v1, s2
	v_mov_b32_e32 v0, 1
	s_nop 1
	global_atomic_add v1, v0, s[0:1]
	s_mov_b32 s15, 0

.LBB0_274:
	s_waitcnt vmcnt(0)
	s_waitcnt vmcnt(0) lgkmcnt(0)
	s_barrier
	s_mov_b64 s[4:5], exec
	v_readlane_b32 s0, v219, 25
	v_readlane_b32 s1, v219, 26
	s_and_b64 s[0:1], s[4:5], s[0:1]
	s_mov_b64 exec, s[0:1]
	s_cbranch_execz .LBB0_326
	v_readlane_b32 s0, v219, 27
	v_readlane_b32 s1, v219, 28
	v_readlane_b32 s2, v219, 29
	v_mov_b32_e32 v0, 0x24000
	s_waitcnt vmcnt(0) lgkmcnt(0)
	buffer_inv sc1
	ds_read_b32 v2, v0
	ds_read_b32 v0, v0 offset:4
	s_lshl_b32 s3, s2, 8
	s_add_i32 s14, s3, 0x2400
	s_add_i32 s3, s3, 0x1400
	v_mov_b32_e32 v1, s3
	s_waitcnt lgkmcnt(0)
	v_readfirstlane_b32 s10, v2
	v_readfirstlane_b32 s11, v0
	v_mov_b32_e32 v0, 1
	s_nop 1
	global_atomic_add v2, v1, v0, s[0:1] sc0
	s_mul_i32 s10, s10, 2
	s_mul_i32 s11, s11, 2
	s_waitcnt vmcnt(0)
	v_readfirstlane_b32 s13, v2
	s_nop 1
	s_add_i32 s13, s13, 1
	s_cmp_lg_u32 s13, s10
	s_cbranch_scc1 .Lnb3_wait
	v_mov_b32_e32 v1, 0x3400
	global_atomic_add v2, v1, v0, s[0:1] sc0
	s_waitcnt vmcnt(0)
	v_readfirstlane_b32 s13, v2
	s_nop 1
	s_add_i32 s13, s13, 1
	s_cmp_lg_u32 s13, s11
	s_cbranch_scc1 .Lnb3_wait
	v_mov_b32_e32 v1, 0x2400
	global_atomic_add v1, v0, s[0:1]
	global_atomic_add v1, v0, s[0:1] offset:256
	global_atomic_add v1, v0, s[0:1] offset:512
	global_atomic_add v1, v0, s[0:1] offset:768
	global_atomic_add v1, v0, s[0:1] offset:1024
	global_atomic_add v1, v0, s[0:1] offset:1280
	global_atomic_add v1, v0, s[0:1] offset:1536
	global_atomic_add v1, v0, s[0:1] offset:1792
	global_atomic_add v1, v0, s[0:1] offset:2048
	global_atomic_add v1, v0, s[0:1] offset:2304
	global_atomic_add v1, v0, s[0:1] offset:2560
	global_atomic_add v1, v0, s[0:1] offset:2816
	global_atomic_add v1, v0, s[0:1] offset:3072
	global_atomic_add v1, v0, s[0:1] offset:3328
	global_atomic_add v1, v0, s[0:1] offset:3584
	global_atomic_add v1, v0, s[0:1] offset:3840

.LBB0_396:
	s_waitcnt vmcnt(0)
	s_waitcnt lgkmcnt(0)
	s_barrier
	s_mov_b64 s[4:5], exec
	v_readlane_b32 s0, v219, 25
	v_readlane_b32 s1, v219, 26
	s_and_b64 s[0:1], s[4:5], s[0:1]
	s_mov_b64 exec, s[0:1]
	s_cbranch_execz .LBB0_448
	v_readlane_b32 s0, v219, 27
	v_readlane_b32 s1, v219, 28
	v_readlane_b32 s2, v219, 29
	v_mov_b32_e32 v0, 0x24000
	s_waitcnt vmcnt(0) lgkmcnt(0)
	buffer_inv sc1
	ds_read_b32 v2, v0
	ds_read_b32 v0, v0 offset:4
	s_lshl_b32 s3, s2, 8
	s_add_i32 s14, s3, 0x2400
	s_add_i32 s3, s3, 0x1400
	v_mov_b32_e32 v1, s3
	s_waitcnt lgkmcnt(0)
	v_readfirstlane_b32 s10, v2
	v_readfirstlane_b32 s11, v0
	v_mov_b32_e32 v0, 1
	s_nop 1
	global_atomic_add v2, v1, v0, s[0:1] sc0
	s_mul_i32 s10, s10, 3
	s_mul_i32 s11, s11, 3
	s_waitcnt vmcnt(0)
	v_readfirstlane_b32 s13, v2
	s_nop 1
	s_add_i32 s13, s13, 1
	s_cmp_lg_u32 s13, s10
	s_cbranch_scc1 .Lnb4_wait
	v_mov_b32_e32 v1, 0x3400
	global_atomic_add v2, v1, v0, s[0:1] sc0
	s_waitcnt vmcnt(0)
	v_readfirstlane_b32 s13, v2
	s_nop 1
	s_add_i32 s13, s13, 1
	s_cmp_lg_u32 s13, s11
	s_cbranch_scc1 .Lnb4_wait
	v_mov_b32_e32 v1, 0x2400
	global_atomic_add v1, v0, s[0:1]
	global_atomic_add v1, v0, s[0:1] offset:256
	global_atomic_add v1, v0, s[0:1] offset:512
	global_atomic_add v1, v0, s[0:1] offset:768
	global_atomic_add v1, v0, s[0:1] offset:1024
	global_atomic_add v1, v0, s[0:1] offset:1280
	global_atomic_add v1, v0, s[0:1] offset:1536
	global_atomic_add v1, v0, s[0:1] offset:1792
	global_atomic_add v1, v0, s[0:1] offset:2048
	global_atomic_add v1, v0, s[0:1] offset:2304
	global_atomic_add v1, v0, s[0:1] offset:2560
	global_atomic_add v1, v0, s[0:1] offset:2816
	global_atomic_add v1, v0, s[0:1] offset:3072
	global_atomic_add v1, v0, s[0:1] offset:3328
	global_atomic_add v1, v0, s[0:1] offset:3584
	global_atomic_add v1, v0, s[0:1] offset:3840

.LBB0_512:
	s_waitcnt vmcnt(0)
	s_waitcnt vmcnt(0) lgkmcnt(0)
	s_barrier
	s_mov_b64 s[4:5], exec
	v_readlane_b32 s0, v219, 25
	v_readlane_b32 s1, v219, 26
	s_and_b64 s[0:1], s[4:5], s[0:1]
	s_mov_b64 exec, s[0:1]
	s_cbranch_execz .LBB0_564
	v_readlane_b32 s0, v219, 27
	v_readlane_b32 s1, v219, 28
	v_readlane_b32 s2, v219, 30
	s_waitcnt vmcnt(0) lgkmcnt(0)
	buffer_inv sc1
	s_and_b32 s2, s2, 31
	s_lshl_b32 s2, s2, 7
	s_add_i32 s2, s2, 64
	v_mov_b32_e32 v1, s2
	v_mov_b32_e32 v0, 1
	s_nop 1
	global_atomic_add v1, v0, s[0:1]
	s_mov_b32 s15, 0
.Lgb5_spin:
	global_load_dword v2, v1, s[0:1] sc1
	s_waitcnt vmcnt(0)
	v_readfirstlane_b32 s13, v2
	s_nop 1
	s_cmp_ge_u32 s13, 16
	s_cbranch_scc1 .Lgb5_done
	s_sleep 1
	s_add_i32 s15, s15, 1
	s_cmp_lt_u32 s15, 0x200000
	s_cbranch_scc1 .Lgb5_spin

.LBB0_564:
	s_or_b64 exec, exec, s[4:5]
	s_waitcnt lgkmcnt(0)
	s_barrier
	s_mov_b64 s[4:5], exec
	v_readlane_b32 s0, v219, 31
	v_readlane_b32 s1, v219, 32
	s_and_b64 s[0:1], s[4:5], s[0:1]
	s_mov_b64 exec, s[0:1]
	s_cbranch_execz .LBB0_577
	v_and_b32_e32 v0, 0x1f8, v144
	v_mov_b32_e32 v65, 0
	v_lshlrev_b32_e32 v64, 1, v0
	v_lshl_add_u64 v[2:3], s[56:57], 0, v[64:65]
	s_mov_b64 s[0:1], 0x8400000
	v_readlane_b32 s8, v219, 9
	v_lshl_add_u64 v[66:67], v[2:3], 0, s[0:1]
	s_mov_b64 s[0:1], 0xa400000
	v_readlane_b32 s9, v219, 10
	v_readlane_b32 s10, v219, 11
	v_readlane_b32 s11, v219, 12
	v_readlane_b32 s12, v219, 13
	v_readlane_b32 s13, v219, 14
	v_lshl_add_u64 v[68:69], v[2:3], 0, s[0:1]
	s_lshl_b32 s0, s58, 3
	v_readlane_b32 s14, v219, 15
	v_readlane_b32 s15, v219, 16
	s_mov_b64 s[8:9], s[12:13]
	s_add_u32 s2, s8, 0x1000
	s_addc_u32 s3, s9, 0
	s_add_u32 s8, s8, 0x2000
	v_lshl_add_u64 v[70:71], s[30:31], 0, v[64:65]
	v_or_b32_e32 v2, 0x200, v0
	s_addc_u32 s9, s9, 0
	v_lshlrev_b32_e32 v64, 2, v0
	v_readlane_b32 s22, v219, 23
	v_readlane_b32 s23, v219, 24
	v_lshl_add_u64 v[72:73], s[2:3], 0, v[64:65]
	v_lshl_add_u64 v[74:75], s[8:9], 0, v[64:65]
	v_lshlrev_b32_e32 v64, 2, v2
	s_mov_b64 s[10:11], s[14:15]
	s_mov_b64 s[6:7], 0x2000
	v_lshl_add_u64 v[76:77], s[2:3], 0, v[64:65]
	v_lshl_add_u64 v[78:79], s[8:9], 0, v[64:65]
	s_and_b32 s98, s78, 31
	s_lshl_b32 s98, s98, 3
	s_lshr_b32 s99, s78, 5
	s_or_b32 s98, s98, s99
	v_lshl_add_u32 v104, s98, 5, v166
	s_lshl_b32 s1, s58, 5
	s_mov_b64 s[12:13], 0
	v_mov_b32_e32 v105, 0xfffff000
	s_movk_i32 s2, 0x3ff
	s_mov_b64 s[14:15], 0x3000
	s_mov_b64 s[22:23], 0x4000
	v_lshlrev_b32_e32 v64, 2, v0
	v_lshlrev_b32_e32 v80, 2, v2
	v_mov_b32_e32 v81, v65
	s_movk_i32 s3, 0xfff
	v_mov_b32_e32 v106, 0x358637bd
	s_mov_b32 s8, 0x800000
	s_movk_i32 s9, 0x7ff
	v_mov_b32_e32 v107, v145
	v_readlane_b32 s16, v219, 17
	v_readlane_b32 s17, v219, 18
	v_readlane_b32 s18, v219, 19
	v_readlane_b32 s19, v219, 20
	v_readlane_b32 s20, v219, 21
	v_readlane_b32 s21, v219, 22
	s_branch .LBB0_567

.Lgb6_spin:
	global_load_dword v2, v1, s[0:1] sc1
	s_waitcnt vmcnt(0)
	v_readfirstlane_b32 s13, v2
	s_nop 1
	s_cmp_ge_u32 s13, 24
	s_cbranch_scc1 .Lgb6_done
	s_sleep 1
	s_add_i32 s15, s15, 1
	s_cmp_lt_u32 s15, 0x200000
	s_cbranch_scc1 .Lgb6_spin

.Lgu0h_skip:
	s_waitcnt vmcnt(0)
	s_waitcnt vmcnt(0) lgkmcnt(0)
	s_barrier
	s_mov_b64 s[4:5], exec
	v_readlane_b32 s0, v219, 25
	v_readlane_b32 s1, v219, 26
	s_and_b64 s[0:1], s[4:5], s[0:1]
	s_mov_b64 exec, s[0:1]
	s_cbranch_execz .LBB0_745
	v_readlane_b32 s0, v219, 27
	v_readlane_b32 s1, v219, 28
	v_readlane_b32 s2, v219, 29
	v_mov_b32_e32 v0, 0x24000
	s_waitcnt vmcnt(0) lgkmcnt(0)
	buffer_inv sc1
	ds_read_b32 v2, v0
	ds_read_b32 v0, v0 offset:4
	s_lshl_b32 s3, s2, 8
	s_add_i32 s14, s3, 0x2400
	s_add_i32 s3, s3, 0x1400
	v_mov_b32_e32 v1, s3
	s_waitcnt lgkmcnt(0)
	v_readfirstlane_b32 s10, v2
	v_readfirstlane_b32 s11, v0
	v_mov_b32_e32 v0, 1
	s_nop 1
	global_atomic_add v2, v1, v0, s[0:1] sc0
	s_mul_i32 s10, s10, 4
	s_mul_i32 s11, s11, 4
	s_waitcnt vmcnt(0)
	v_readfirstlane_b32 s13, v2
	s_nop 1
	s_add_i32 s13, s13, 1
	s_cmp_lg_u32 s13, s10
	s_cbranch_scc1 .Lnb7_wait
	v_mov_b32_e32 v1, 0x3400
	global_atomic_add v2, v1, v0, s[0:1] sc0
	s_waitcnt vmcnt(0)
	v_readfirstlane_b32 s13, v2
	s_nop 1
	s_add_i32 s13, s13, 1
	s_cmp_lg_u32 s13, s11
	s_cbranch_scc1 .Lnb7_wait
	v_mov_b32_e32 v1, 0x2400
	global_atomic_add v1, v0, s[0:1]
	global_atomic_add v1, v0, s[0:1] offset:256
	global_atomic_add v1, v0, s[0:1] offset:512
	global_atomic_add v1, v0, s[0:1] offset:768
	global_atomic_add v1, v0, s[0:1] offset:1024
	global_atomic_add v1, v0, s[0:1] offset:1280
	global_atomic_add v1, v0, s[0:1] offset:1536
	global_atomic_add v1, v0, s[0:1] offset:1792
	global_atomic_add v1, v0, s[0:1] offset:2048
	global_atomic_add v1, v0, s[0:1] offset:2304
	global_atomic_add v1, v0, s[0:1] offset:2560
	global_atomic_add v1, v0, s[0:1] offset:2816
	global_atomic_add v1, v0, s[0:1] offset:3072
	global_atomic_add v1, v0, s[0:1] offset:3328
	global_atomic_add v1, v0, s[0:1] offset:3584
	global_atomic_add v1, v0, s[0:1] offset:3840

.LBB0_809:
	s_waitcnt vmcnt(0)
	s_waitcnt vmcnt(0) lgkmcnt(0)
	s_barrier
	s_mov_b64 s[6:7], exec
	v_readlane_b32 s0, v219, 25
	v_readlane_b32 s1, v219, 26
	s_and_b64 s[0:1], s[6:7], s[0:1]
	s_mov_b64 exec, s[0:1]
	s_cbranch_execz .LBB0_861
	v_readlane_b32 s0, v219, 27
	v_readlane_b32 s1, v219, 28
	v_readlane_b32 s2, v219, 30
	s_waitcnt vmcnt(0) lgkmcnt(0)
	buffer_inv sc1
	s_and_b32 s2, s2, 31
	s_lshl_b32 s2, s2, 7
	s_add_i32 s2, s2, 64
	v_mov_b32_e32 v1, s2
	v_mov_b32_e32 v0, 1
	s_nop 1
	global_atomic_add v1, v0, s[0:1]
	s_mov_b32 s15, 0
.Lgb8_spin:
	global_load_dword v2, v1, s[0:1] sc1
	s_waitcnt vmcnt(0)
	v_readfirstlane_b32 s13, v2
	s_nop 1
	s_cmp_ge_u32 s13, 32
	s_cbranch_scc1 .Lgb8_done
	s_sleep 1
	s_add_i32 s15, s15, 1
	s_cmp_lt_u32 s15, 0x200000
	s_cbranch_scc1 .Lgb8_spin

.LBB0_861:
	s_or_b64 exec, exec, s[6:7]
	s_waitcnt lgkmcnt(0)
	s_barrier
	s_mov_b64 s[6:7], exec
	v_readlane_b32 s0, v219, 31
	v_readlane_b32 s1, v219, 32
	s_and_b64 s[0:1], s[6:7], s[0:1]
	s_mov_b64 exec, s[0:1]
	s_cbranch_execz .LBB0_866
	v_and_b32_e32 v0, 0x1f8, v144
	v_mov_b32_e32 v65, 0
	v_lshlrev_b32_e32 v64, 1, v0
	v_lshl_add_u64 v[2:3], s[56:57], 0, v[64:65]
	s_mov_b64 s[0:1], 0xa400000
	v_readlane_b32 s8, v219, 9
	v_lshl_add_u64 v[66:67], v[2:3], 0, s[0:1]
	s_mov_b64 s[0:1], 0x8400000
	v_readlane_b32 s9, v219, 10
	v_readlane_b32 s10, v219, 11
	v_readlane_b32 s11, v219, 12
	v_readlane_b32 s12, v219, 13
	v_readlane_b32 s13, v219, 14
	v_lshl_add_u64 v[68:69], v[2:3], 0, s[0:1]
	s_lshl_b32 s0, s58, 3
	v_readlane_b32 s14, v219, 15
	v_readlane_b32 s15, v219, 16
	s_mov_b64 s[8:9], s[12:13]
	s_add_u32 s2, s8, 0x3000
	s_addc_u32 s3, s9, 0
	s_add_u32 s4, s8, 0x4000
	v_lshl_add_u64 v[70:71], s[30:31], 0, v[64:65]
	v_or_b32_e32 v2, 0x200, v0
	s_addc_u32 s5, s9, 0
	v_lshlrev_b32_e32 v64, 2, v0
	v_lshl_add_u64 v[72:73], s[2:3], 0, v[64:65]
	v_lshl_add_u64 v[74:75], s[4:5], 0, v[64:65]
	v_lshlrev_b32_e32 v64, 2, v2
	s_mov_b64 s[10:11], s[14:15]
	v_lshl_add_u64 v[76:77], s[2:3], 0, v[64:65]
	v_lshl_add_u64 v[78:79], s[4:5], 0, v[64:65]
	s_and_b32 s98, s78, 31
	s_lshl_b32 s98, s98, 3
	s_lshr_b32 s99, s78, 5
	s_or_b32 s98, s98, s99
	v_lshl_add_u32 v102, s98, 5, v166
	s_lshl_b32 s1, s58, 5
	s_mov_b64 s[8:9], 0
	v_mov_b32_e32 v103, 0xfffff000
	s_movk_i32 s2, 0x3ff
	s_mov_b64 s[12:13], 0x5000
	s_mov_b64 s[14:15], 0x1000
	v_lshlrev_b32_e32 v64, 2, v0
	v_lshlrev_b32_e32 v80, 2, v2
	v_mov_b32_e32 v81, v65
	v_mov_b32_e32 v104, 0x358637bd
	s_mov_b32 s3, 0x800000
	s_movk_i32 s4, 0x7ff
	v_mov_b32_e32 v105, v145
	v_readlane_b32 s16, v219, 17
	v_readlane_b32 s17, v219, 18
	v_readlane_b32 s18, v219, 19
	v_readlane_b32 s19, v219, 20
	v_readlane_b32 s20, v219, 21
	v_readlane_b32 s21, v219, 22
	v_readlane_b32 s22, v219, 23
	v_readlane_b32 s23, v219, 24

.LBB0_866:
	s_or_b64 exec, exec, s[6:7]
	s_waitcnt vmcnt(0)
	s_barrier
	s_mov_b64 s[6:7], exec
	v_readlane_b32 s0, v219, 25
	v_readlane_b32 s1, v219, 26
	s_and_b64 s[0:1], s[6:7], s[0:1]
	s_mov_b64 exec, s[0:1]
	s_cbranch_execz .LBB0_918
	v_readlane_b32 s0, v219, 27
	v_readlane_b32 s1, v219, 28
	v_readlane_b32 s2, v219, 29
	v_mov_b32_e32 v0, 0x24000
	s_waitcnt vmcnt(0) lgkmcnt(0)
	buffer_inv sc1
	ds_read_b32 v2, v0
	ds_read_b32 v0, v0 offset:4
	s_lshl_b32 s3, s2, 8
	s_add_i32 s14, s3, 0x2400
	s_add_i32 s3, s3, 0x1400
	v_mov_b32_e32 v1, s3
	s_waitcnt lgkmcnt(0)
	v_readfirstlane_b32 s10, v2
	v_readfirstlane_b32 s11, v0
	v_mov_b32_e32 v0, 1
	s_nop 1
	global_atomic_add v2, v1, v0, s[0:1] sc0
	s_mul_i32 s10, s10, 5
	s_mul_i32 s11, s11, 5
	s_waitcnt vmcnt(0)
	v_readfirstlane_b32 s13, v2
	s_nop 1
	s_add_i32 s13, s13, 1
	s_cmp_lg_u32 s13, s10
	s_cbranch_scc1 .Lnb9_wait
	v_mov_b32_e32 v1, 0x3400
	global_atomic_add v2, v1, v0, s[0:1] sc0
	s_waitcnt vmcnt(0)
	v_readfirstlane_b32 s13, v2
	s_nop 1
	s_add_i32 s13, s13, 1
	s_cmp_lg_u32 s13, s11
	s_cbranch_scc1 .Lnb9_wait
	v_mov_b32_e32 v1, 0x2400
	global_atomic_add v1, v0, s[0:1]
	global_atomic_add v1, v0, s[0:1] offset:256
	global_atomic_add v1, v0, s[0:1] offset:512
	global_atomic_add v1, v0, s[0:1] offset:768
	global_atomic_add v1, v0, s[0:1] offset:1024
	global_atomic_add v1, v0, s[0:1] offset:1280
	global_atomic_add v1, v0, s[0:1] offset:1536
	global_atomic_add v1, v0, s[0:1] offset:1792
	global_atomic_add v1, v0, s[0:1] offset:2048
	global_atomic_add v1, v0, s[0:1] offset:2304
	global_atomic_add v1, v0, s[0:1] offset:2560
	global_atomic_add v1, v0, s[0:1] offset:2816
	global_atomic_add v1, v0, s[0:1] offset:3072
	global_atomic_add v1, v0, s[0:1] offset:3328
	global_atomic_add v1, v0, s[0:1] offset:3584
	global_atomic_add v1, v0, s[0:1] offset:3840

.LBB0_1035:
	s_waitcnt vmcnt(0)
	s_waitcnt vmcnt(0) lgkmcnt(0)
	s_barrier
	s_mov_b64 s[6:7], exec
	v_readlane_b32 s0, v219, 25
	v_readlane_b32 s1, v219, 26
	s_and_b64 s[0:1], s[6:7], s[0:1]
	s_mov_b64 exec, s[0:1]
	s_cbranch_execz .LBB0_1087
	v_readlane_b32 s0, v219, 27
	v_readlane_b32 s1, v219, 28
	v_readlane_b32 s2, v219, 29
	v_mov_b32_e32 v0, 0x24000
	s_waitcnt vmcnt(0) lgkmcnt(0)
	buffer_inv sc1
	ds_read_b32 v2, v0
	ds_read_b32 v0, v0 offset:4
	s_lshl_b32 s3, s2, 8
	s_add_i32 s14, s3, 0x2400
	s_add_i32 s3, s3, 0x1400
	v_mov_b32_e32 v1, s3
	s_waitcnt lgkmcnt(0)
	v_readfirstlane_b32 s10, v2
	v_readfirstlane_b32 s11, v0
	v_mov_b32_e32 v0, 1
	s_nop 1
	global_atomic_add v2, v1, v0, s[0:1] sc0
	s_mul_i32 s10, s10, 6
	s_mul_i32 s11, s11, 6
	s_waitcnt vmcnt(0)
	v_readfirstlane_b32 s13, v2
	s_nop 1
	s_add_i32 s13, s13, 1
	s_cmp_lg_u32 s13, s10
	s_cbranch_scc1 .Lnb10_wait
	v_mov_b32_e32 v1, 0x3400
	global_atomic_add v2, v1, v0, s[0:1] sc0
	s_waitcnt vmcnt(0)
	v_readfirstlane_b32 s13, v2
	s_nop 1
	s_add_i32 s13, s13, 1
	s_cmp_lg_u32 s13, s11
	s_cbranch_scc1 .Lnb10_wait
	v_mov_b32_e32 v1, 0x2400
	global_atomic_add v1, v0, s[0:1]
	global_atomic_add v1, v0, s[0:1] offset:256
	global_atomic_add v1, v0, s[0:1] offset:512
	global_atomic_add v1, v0, s[0:1] offset:768
	global_atomic_add v1, v0, s[0:1] offset:1024
	global_atomic_add v1, v0, s[0:1] offset:1280
	global_atomic_add v1, v0, s[0:1] offset:1536
	global_atomic_add v1, v0, s[0:1] offset:1792
	global_atomic_add v1, v0, s[0:1] offset:2048
	global_atomic_add v1, v0, s[0:1] offset:2304
	global_atomic_add v1, v0, s[0:1] offset:2560
	global_atomic_add v1, v0, s[0:1] offset:2816
	global_atomic_add v1, v0, s[0:1] offset:3072
	global_atomic_add v1, v0, s[0:1] offset:3328
	global_atomic_add v1, v0, s[0:1] offset:3584
	global_atomic_add v1, v0, s[0:1] offset:3840

.LBB0_1120:
	s_waitcnt vmcnt(0)
	s_barrier
	s_mov_b64 s[6:7], exec
	v_readlane_b32 s0, v219, 25
	v_readlane_b32 s1, v219, 26
	s_and_b64 s[0:1], s[6:7], s[0:1]
	s_mov_b64 exec, s[0:1]
	s_cbranch_execz .LBB0_1172
	v_readlane_b32 s0, v219, 27
	v_readlane_b32 s1, v219, 28
	v_readlane_b32 s2, v219, 29
	v_mov_b32_e32 v0, 0x24000
	s_waitcnt vmcnt(0) lgkmcnt(0)
	buffer_inv sc1
	ds_read_b32 v2, v0
	ds_read_b32 v0, v0 offset:4
	s_lshl_b32 s3, s2, 8
	s_add_i32 s14, s3, 0x2400
	s_add_i32 s3, s3, 0x1400
	v_mov_b32_e32 v1, s3
	s_waitcnt lgkmcnt(0)
	v_readfirstlane_b32 s10, v2
	v_readfirstlane_b32 s11, v0
	v_mov_b32_e32 v0, 1
	s_nop 1
	global_atomic_add v2, v1, v0, s[0:1] sc0
	s_mul_i32 s10, s10, 7
	s_mul_i32 s11, s11, 7
	s_waitcnt vmcnt(0)
	v_readfirstlane_b32 s13, v2
	s_nop 1
	s_add_i32 s13, s13, 1
	s_cmp_lg_u32 s13, s10
	s_cbranch_scc1 .Lnb11_wait
	v_mov_b32_e32 v1, 0x3400
	global_atomic_add v2, v1, v0, s[0:1] sc0
	s_waitcnt vmcnt(0)
	v_readfirstlane_b32 s13, v2
	s_nop 1
	s_add_i32 s13, s13, 1
	s_cmp_lg_u32 s13, s11
	s_cbranch_scc1 .Lnb11_wait
	v_mov_b32_e32 v1, 0x2400
	global_atomic_add v1, v0, s[0:1]
	global_atomic_add v1, v0, s[0:1] offset:256
	global_atomic_add v1, v0, s[0:1] offset:512
	global_atomic_add v1, v0, s[0:1] offset:768
	global_atomic_add v1, v0, s[0:1] offset:1024
	global_atomic_add v1, v0, s[0:1] offset:1280
	global_atomic_add v1, v0, s[0:1] offset:1536
	global_atomic_add v1, v0, s[0:1] offset:1792
	global_atomic_add v1, v0, s[0:1] offset:2048
	global_atomic_add v1, v0, s[0:1] offset:2304
	global_atomic_add v1, v0, s[0:1] offset:2560
	global_atomic_add v1, v0, s[0:1] offset:2816
	global_atomic_add v1, v0, s[0:1] offset:3072
	global_atomic_add v1, v0, s[0:1] offset:3328
	global_atomic_add v1, v0, s[0:1] offset:3584
	global_atomic_add v1, v0, s[0:1] offset:3840

.Lgb12_spin:
	global_load_dword v2, v1, s[0:1] sc1
	s_waitcnt vmcnt(0)
	v_readfirstlane_b32 s13, v2
	s_nop 1
	s_cmp_ge_u32 s13, 40
	s_cbranch_scc1 .Lgb12_done
	s_sleep 1
	s_add_i32 s15, s15, 1
	s_cmp_lt_u32 s15, 0x200000
	s_cbranch_scc1 .Lgb12_spin

.LBB0_1288:
	s_or_b64 exec, exec, s[6:7]
	s_waitcnt lgkmcnt(0)
	s_barrier
	s_mov_b64 s[6:7], exec
	v_readlane_b32 s0, v219, 31
	v_readlane_b32 s1, v219, 32
	s_and_b64 s[0:1], s[6:7], s[0:1]
	s_mov_b64 exec, s[0:1]
	s_cbranch_execz .LBB0_1293
	v_and_b32_e32 v0, 0x1f8, v144
	v_mov_b32_e32 v65, 0
	v_lshlrev_b32_e32 v64, 1, v0
	v_lshl_add_u64 v[2:3], s[56:57], 0, v[64:65]
	s_mov_b64 s[0:1], 0x8400000
	v_readlane_b32 s8, v219, 9
	v_lshl_add_u64 v[66:67], v[2:3], 0, s[0:1]
	s_mov_b64 s[0:1], 0xa400000
	v_readlane_b32 s12, v219, 13
	v_readlane_b32 s13, v219, 14
	v_lshl_add_u64 v[68:69], v[2:3], 0, s[0:1]
	s_lshl_b32 s0, s58, 3
	s_mov_b64 s[4:5], s[12:13]
	s_add_u32 s2, s4, 0x5000
	s_addc_u32 s3, s5, 0
	s_add_u32 s4, s4, 0x6000
	v_lshl_add_u64 v[70:71], s[30:31], 0, v[64:65]
	v_or_b32_e32 v2, 0x200, v0
	s_addc_u32 s5, s5, 0
	v_lshlrev_b32_e32 v64, 2, v0
	v_readlane_b32 s9, v219, 10
	v_readlane_b32 s14, v219, 15
	v_readlane_b32 s15, v219, 16
	v_readlane_b32 s18, v219, 19
	v_readlane_b32 s19, v219, 20
	v_lshl_add_u64 v[72:73], s[2:3], 0, v[64:65]
	v_lshl_add_u64 v[74:75], s[4:5], 0, v[64:65]
	v_lshlrev_b32_e32 v64, 2, v2
	v_lshl_add_u64 v[76:77], s[2:3], 0, v[64:65]
	v_lshl_add_u64 v[78:79], s[4:5], 0, v[64:65]
	s_and_b32 s98, s78, 31
	s_lshl_b32 s98, s98, 3
	s_lshr_b32 s99, s78, 5
	s_or_b32 s98, s98, s99
	v_lshl_add_u32 v102, s98, 5, v166
	s_lshl_b32 s1, s58, 5
	s_mov_b64 s[8:9], 0
	v_mov_b32_e32 v103, 0xfffff000
	s_movk_i32 s2, 0x3ff
	s_mov_b64 s[12:13], 0x2000
	s_mov_b64 s[14:15], 0x3000
	s_mov_b64 s[18:19], 0x4000
	v_lshlrev_b32_e32 v64, 2, v0
	v_lshlrev_b32_e32 v80, 2, v2
	v_mov_b32_e32 v81, v65
	v_mov_b32_e32 v104, 0x358637bd
	s_mov_b32 s3, 0x800000
	s_movk_i32 s4, 0x7ff
	v_mov_b32_e32 v105, v145
	v_readlane_b32 s10, v219, 11
	v_readlane_b32 s11, v219, 12
	v_readlane_b32 s16, v219, 17
	v_readlane_b32 s17, v219, 18
	v_readlane_b32 s20, v219, 21
	v_readlane_b32 s21, v219, 22
	v_readlane_b32 s22, v219, 23
	v_readlane_b32 s23, v219, 24

.LBB0_1293:
	s_or_b64 exec, exec, s[6:7]
	s_waitcnt vmcnt(0)
	s_barrier
	s_mov_b64 s[6:7], exec
	v_readlane_b32 s0, v219, 25
	v_readlane_b32 s1, v219, 26
	s_and_b64 s[0:1], s[6:7], s[0:1]
	s_mov_b64 exec, s[0:1]
	s_cbranch_execz .LBB0_1345
	v_readlane_b32 s0, v219, 27
	v_readlane_b32 s1, v219, 28
	v_readlane_b32 s2, v219, 30
	s_waitcnt vmcnt(0) lgkmcnt(0)
	buffer_inv sc1
	s_and_b32 s2, s2, 31
	s_lshl_b32 s2, s2, 7
	s_add_i32 s2, s2, 64
	v_mov_b32_e32 v1, s2
	v_mov_b32_e32 v0, 1
	s_nop 1
	global_atomic_add v1, v0, s[0:1]
	s_mov_b32 s15, 0
.Lgb13_spin:
	global_load_dword v2, v1, s[0:1] sc1
	s_waitcnt vmcnt(0)
	v_readfirstlane_b32 s13, v2
	s_nop 1
	s_cmp_ge_u32 s13, 48
	s_cbranch_scc1 .Lgb13_done
	s_sleep 1
	s_add_i32 s15, s15, 1
	s_cmp_lt_u32 s15, 0x200000
	s_cbranch_scc1 .Lgb13_spin

.Lgb14_spin:
	global_load_dword v2, v1, s[0:1] sc1
	s_waitcnt vmcnt(0)
	v_readfirstlane_b32 s13, v2
	s_nop 1
	s_cmp_ge_u32 s13, 56
	s_cbranch_scc1 .Lgb14_done
	s_sleep 1
	s_add_i32 s15, s15, 1
	s_cmp_lt_u32 s15, 0x200000
	s_cbranch_scc1 .Lgb14_spin

.Lgb15_spin:
	global_load_dword v2, v1, s[0:1] sc1
	s_waitcnt vmcnt(0)
	v_readfirstlane_b32 s13, v2
	s_nop 1
	s_cmp_ge_u32 s13, 64
	s_cbranch_scc1 .Lgb15_done
	s_sleep 1
	s_add_i32 s15, s15, 1
	s_cmp_lt_u32 s15, 0x200000
	s_cbranch_scc1 .Lgb15_spin

.LBB0_1577:
	s_or_b64 exec, exec, s[4:5]
	v_readlane_b32 s2, v219, 31
	v_readlane_b32 s3, v219, 32
	s_waitcnt lgkmcnt(0)
	s_barrier
	s_and_saveexec_b64 s[0:1], s[2:3]
	s_cbranch_execz .LBB0_1582
	v_and_b32_e32 v0, 0x1f8, v144
	v_mov_b32_e32 v33, 0
	v_lshlrev_b32_e32 v32, 1, v0
	v_readlane_b32 s8, v219, 9
	v_lshl_add_u64 v[2:3], s[56:57], 0, v[32:33]
	s_mov_b64 s[0:1], 0xa400000
	v_readlane_b32 s9, v219, 10
	v_readlane_b32 s12, v219, 13
	v_readlane_b32 s13, v219, 14
	v_lshl_add_u64 v[34:35], v[2:3], 0, s[0:1]
	s_mov_b64 s[0:1], 0x8400000
	s_lshl_b32 s4, s58, 3
	s_mov_b64 s[8:9], s[12:13]
	v_lshl_add_u64 v[36:37], v[2:3], 0, s[0:1]
	v_or_b32_e32 v2, 0x200, v0
	s_add_u32 s0, s8, 0x7000
	s_addc_u32 s1, s9, 0
	v_lshlrev_b32_e32 v32, 2, v0
	v_lshlrev_b32_e32 v4, 2, v2
	v_mov_b32_e32 v5, v33
	v_lshl_add_u64 v[38:39], s[0:1], 0, v[32:33]
	v_lshl_add_u64 v[40:41], s[0:1], 0, v[4:5]
	v_lshl_add_u64 v[42:43], s[54:55], 0, v[32:33]
	s_and_b32 s98, s78, 31
	s_lshl_b32 s98, s98, 3
	s_lshr_b32 s99, s78, 5
	s_or_b32 s98, s98, s99
	v_lshl_add_u32 v48, s98, 5, v166
	s_lshl_b32 s5, s58, 5
	s_mov_b64 s[0:1], 0
	v_mov_b32_e32 v49, 0xfffff000
	s_movk_i32 s6, 0x3ff
	s_mov_b64 s[2:3], 0x5000
	v_lshlrev_b32_e32 v32, 2, v0
	v_lshlrev_b32_e32 v44, 2, v2
	v_mov_b32_e32 v45, v33
	v_mov_b32_e32 v50, 0x358637bd
	s_mov_b32 s7, 0x800000
	s_movk_i32 s8, 0x7ff
	v_readlane_b32 s10, v219, 11
	v_readlane_b32 s11, v219, 12
	v_readlane_b32 s14, v219, 15
	v_readlane_b32 s15, v219, 16
	v_readlane_b32 s16, v219, 17
	v_readlane_b32 s17, v219, 18
	v_readlane_b32 s18, v219, 19
	v_readlane_b32 s19, v219, 20
	v_readlane_b32 s20, v219, 21
	v_readlane_b32 s21, v219, 22
	v_readlane_b32 s22, v219, 23
	v_readlane_b32 s23, v219, 24
